# peerq phase: one of the two co-resident blocks per CU (HW_ID threadgroup bit) at s_setprio 1 to desynchronise them; reset at next phase
# baseline (speedup 1.0000x reference)
.LBB0_32:
	s_getreg_b32 s98, hwreg(HW_REG_HW_ID, 16, 4)
	s_and_b32 s98, s98, 1
	s_cmp_eq_u32 s98, 0
	s_cbranch_scc1 .Lpq_lo
	s_setprio 1
